# attention: local-K row loads issued inside the final ctx pass (after the 4th PV group, into released registers) so their round trip overlaps the remaining softmax/PV work
# speedup vs baseline: 1.0190x; 1.0073x over previous
; #define AH_LDK(c, bufi) do { kf[bufi][0] = *(const LAS bf16x8*)(lds + kaddr0 + (c) * kcs); kf[bufi][1] = *(const LAS bf16x8*)(lds + kaddr1 + (c) * kcs); \
;         kf[bufi][2] = *(const LAS bf16x8*)(lds + kaddr0 + (c) * kcs + 512); kf[bufi][3] = *(const LAS bf16x8*)(lds + kaddr1 + (c) * kcs + 512); } while (0)
; template <bool LOC> ...
;     ...
;     AH_LDK(0, 0);
; #pragma unroll
;     for (int c = 0; c < 8; ++c) {
;         if (c < 7) AH_LDK(c + 1, (c + 1) & 1);
;         __builtin_amdgcn_sched_barrier(0);
;         f32x4 t0 = (f32x4){0.f, 0.f, 0.f, 0.f}, t1 = (f32x4){0.f, 0.f, 0.f, 0.f};
;         t0 = __builtin_amdgcn_mfma_f32_16x16x32_bf16(kf[c & 1][0], q0, t0, 0, 0, 0); t1 = __builtin_amdgcn_mfma_f32_16x16x32_bf16(kf[c & 1][2], q0, t1, 0, 0, 0);
;         t0 = __builtin_amdgcn_mfma_f32_16x16x32_bf16(kf[c & 1][1], q1, t0, 0, 0, 0); t1 = __builtin_amdgcn_mfma_f32_16x16x32_bf16(kf[c & 1][3], q1, t1, 0, 0, 0);
; #pragma unroll
;         for (int e = 0; e < 8; ++e) { const float a = (e < 4) ? t0[e] : t1[e - 4];
;             if (LOC) { const float bv = bp[c * RPB_PITCH + e]; const bool ok = (e >= elo) && (e < elo + 16); s[c][e] = ok ? (a * SC + bv) : -INFINITY; }
;             else s[c][e] = a * SC; }
;         __builtin_amdgcn_sched_barrier(0);
;     }
;     ...
;     float m2 = mx;
; #pragma unroll
;     for (int c = 0; c < 8; ++c)
; #pragma unroll
;         for (int e = 0; e < 8; ++e) m2 = fmaxf(m2, s[c][e]);
;     m2 = fmaxf(m2, __shfl_xor(m2, 16)); m2 = fmaxf(m2, __shfl_xor(m2, 32));
.Lqjoin_299:
	ds_read_b128 v[8:11], v132
	ds_read_b128 v[12:15], v132 offset:512
	ds_read_b128 v[16:19], v133
	ds_read_b128 v[20:23], v133 offset:512
	ds_read_b128 v[24:27], v132 offset:4096
	ds_read_b128 v[28:31], v132 offset:4608
	ds_read_b128 v[32:35], v133 offset:4096
	ds_read_b128 v[36:39], v133 offset:4608
	s_waitcnt lgkmcnt(7)
	v_mfma_f32_16x16x32_bf16 v[8:11], v[8:11], v[4:7], 0
	s_waitcnt lgkmcnt(5)
	v_mfma_f32_16x16x32_bf16 v[68:71], v[16:19], v[0:3], v[8:11]
	v_mfma_f32_16x16x32_bf16 v[8:11], v[12:15], v[4:7], 0
	s_waitcnt lgkmcnt(4)
	v_mfma_f32_16x16x32_bf16 v[64:67], v[20:23], v[0:3], v[8:11]
	s_nop 4
	ds_read_b128 v[8:11], v132 offset:8192
	ds_read_b128 v[12:15], v132 offset:8704
	ds_read_b128 v[16:19], v133 offset:8192
	ds_read_b128 v[20:23], v133 offset:8704
	s_waitcnt lgkmcnt(4)
	v_mfma_f32_16x16x32_bf16 v[24:27], v[24:27], v[4:7], 0
	v_mfma_f32_16x16x32_bf16 v[60:63], v[32:35], v[0:3], v[24:27]
	v_mfma_f32_16x16x32_bf16 v[24:27], v[28:31], v[4:7], 0
	v_mfma_f32_16x16x32_bf16 v[56:59], v[36:39], v[0:3], v[24:27]
	s_nop 4
	ds_read_b128 v[24:27], v132 offset:12288
	ds_read_b128 v[28:31], v132 offset:12800
	ds_read_b128 v[32:35], v133 offset:12288
	ds_read_b128 v[36:39], v133 offset:12800
	s_waitcnt lgkmcnt(4)
	v_mfma_f32_16x16x32_bf16 v[8:11], v[8:11], v[4:7], 0
	v_mfma_f32_16x16x32_bf16 v[52:55], v[16:19], v[0:3], v[8:11]
	v_mfma_f32_16x16x32_bf16 v[8:11], v[12:15], v[4:7], 0
	v_mfma_f32_16x16x32_bf16 v[48:51], v[20:23], v[0:3], v[8:11]
	s_nop 4
	ds_read_b128 v[8:11], v132 offset:16384
	ds_read_b128 v[12:15], v132 offset:16896
	ds_read_b128 v[16:19], v133 offset:16384
	ds_read_b128 v[20:23], v133 offset:16896
	s_waitcnt lgkmcnt(4)
	v_mfma_f32_16x16x32_bf16 v[24:27], v[24:27], v[4:7], 0
	v_mfma_f32_16x16x32_bf16 v[44:47], v[32:35], v[0:3], v[24:27]
	v_mfma_f32_16x16x32_bf16 v[24:27], v[28:31], v[4:7], 0
	v_mfma_f32_16x16x32_bf16 v[40:43], v[36:39], v[0:3], v[24:27]
	s_nop 4
	ds_read_b128 v[24:27], v132 offset:20480
	ds_read_b128 v[152:155], v132 offset:20992
	ds_read_b128 v[28:31], v133 offset:20480
	ds_read_b128 v[170:173], v133 offset:20992
	s_waitcnt lgkmcnt(4)
	v_mfma_f32_16x16x32_bf16 v[8:11], v[8:11], v[4:7], 0
	v_mfma_f32_16x16x32_bf16 v[36:39], v[16:19], v[0:3], v[8:11]
	v_mfma_f32_16x16x32_bf16 v[8:11], v[12:15], v[4:7], 0
	v_mfma_f32_16x16x32_bf16 v[32:35], v[20:23], v[0:3], v[8:11]
	s_nop 4
	ds_read_b128 v[8:11], v132 offset:24576
	ds_read_b128 v[12:15], v132 offset:25088
	ds_read_b128 v[16:19], v133 offset:24576
	ds_read_b128 v[174:177], v133 offset:25088
	s_waitcnt lgkmcnt(4)
	v_mfma_f32_16x16x32_bf16 v[20:23], v[24:27], v[4:7], 0
	v_mfma_f32_16x16x32_bf16 v[28:31], v[28:31], v[0:3], v[20:23]
	v_mfma_f32_16x16x32_bf16 v[20:23], v[152:155], v[4:7], 0
	v_mfma_f32_16x16x32_bf16 v[24:27], v[170:173], v[0:3], v[20:23]
	s_nop 4
	ds_read_b128 v[152:155], v132 offset:28672
	ds_read_b128 v[170:173], v132 offset:29184
	ds_read_b128 v[178:181], v133 offset:28672
	ds_read_b128 v[182:185], v133 offset:29184
	s_waitcnt lgkmcnt(0)
	v_mfma_f32_16x16x32_bf16 v[8:11], v[8:11], v[4:7], 0
	v_mfma_f32_16x16x32_bf16 v[20:23], v[16:19], v[0:3], v[8:11]
	v_mfma_f32_16x16x32_bf16 v[8:11], v[12:15], v[4:7], 0
	v_mfma_f32_16x16x32_bf16 v[16:19], v[174:177], v[0:3], v[8:11]
	s_nop 4
	v_mfma_f32_16x16x32_bf16 v[8:11], v[152:155], v[4:7], 0
	v_mfma_f32_16x16x32_bf16 v[12:15], v[178:181], v[0:3], v[8:11]
	v_mfma_f32_16x16x32_bf16 v[8:11], v[170:173], v[4:7], 0
	v_mfma_f32_16x16x32_bf16 v[8:11], v[182:185], v[0:3], v[8:11]
	s_nop 4
	s_mov_b32 s30, 0xff800000
	v_max3_f32 v97, v68, s30, v69
	v_max3_f32 v97, v97, v70, v71
	v_max3_f32 v97, v97, v64, v65
	v_max3_f32 v97, v97, v66, v67
	v_max3_f32 v97, v97, v60, v61
	v_max3_f32 v97, v97, v62, v63
	v_max3_f32 v97, v97, v56, v57
	v_max3_f32 v97, v97, v58, v59
	v_max3_f32 v97, v97, v52, v53
	v_max3_f32 v97, v97, v54, v55
	v_max3_f32 v97, v97, v48, v49
	v_max3_f32 v97, v97, v50, v51
	v_max3_f32 v97, v97, v44, v45
	v_max3_f32 v97, v97, v46, v47
	v_max3_f32 v97, v97, v40, v41
	v_max3_f32 v97, v97, v42, v43
	v_max3_f32 v97, v97, v36, v37
	v_max3_f32 v97, v97, v38, v39
	v_max3_f32 v97, v97, v32, v33
	v_max3_f32 v97, v97, v34, v35
	v_max3_f32 v97, v97, v28, v29
	v_max3_f32 v97, v97, v30, v31
	v_max3_f32 v97, v97, v24, v25
	v_max3_f32 v97, v97, v26, v27
	v_max3_f32 v97, v97, v20, v21
	v_max3_f32 v97, v97, v22, v23
	v_max3_f32 v97, v97, v16, v17
	v_max3_f32 v97, v97, v18, v19
	v_max3_f32 v97, v97, v12, v13
	v_max3_f32 v97, v97, v14, v15
	v_max3_f32 v97, v97, v8, v9
	v_max3_f32 v97, v97, v10, v11
	v_mul_f32_e32 v97, 0x3e38aa3b, v97
	ds_bpermute_b32 v99, v114, v97
	ds_read_b128 v[152:155], v134 offset:32768
	ds_read_b128 v[170:173], v134 offset:40960
	ds_read_b128 v[174:177], v134 offset:49152
	ds_read_b128 v[178:181], v134 offset:57344
	ds_read_b128 v[182:185], v135 offset:32768
	ds_read_b128 v[186:189], v135 offset:40960
	ds_read_b128 v[190:193], v135 offset:49152
	ds_read_b128 v[194:197], v135 offset:57344
	s_waitcnt lgkmcnt(8)
	v_max_f32_e32 v99, v99, v99
	v_max_f32_e32 v97, v97, v99
	ds_bpermute_b32 v99, v115, v97
	s_waitcnt lgkmcnt(0)
; __device__ __forceinline__ unsigned cvt_pk_bf16(float lo, float hi) { const f32x2 v = (f32x2){lo, hi}; return __builtin_bit_cast(unsigned, __builtin_convertvector(v, bf16v2)); }
; #define AH_LDV(c, bufi) do { const int vaddr = vrow + (((vchunk0 + (c) * vcs + g) ^ qi) << 4); _Pragma("unroll") for (int dt = 0; dt < 4; ++dt) vf[bufi][dt] = *(const LAS bf16x8*)(lds + vaddr + dt * vpitch_dt); } while (0)
; template <bool LOC> ...
;     ...
;     const float alpha = __builtin_amdgcn_exp2f(mx - m2);
;     mx = m2; lsum *= alpha;
; #pragma unroll
;     for (int dt = 0; dt < 4; ++dt) o[dt] = o[dt] * alpha;
;     bf16x8 vf[2][4];
;     ...
;     AH_LDV(0, 0);
; #pragma unroll
;     for (int c = 0; c < 8; ++c) {
;         if (c < 7) AH_LDV(c + 1, (c + 1) & 1);
;         __builtin_amdgcn_sched_barrier(0);
;         float pe[8];
; #pragma unroll
;         for (int e = 0; e < 8; ++e) { pe[e] = __builtin_amdgcn_exp2f(s[c][e] - mx); lsum += pe[e]; }
;         u32x4 pw; pw.x = cvt_pk_bf16(pe[0], pe[1]); pw.y = cvt_pk_bf16(pe[2], pe[3]); pw.z = cvt_pk_bf16(pe[4], pe[5]); pw.w = cvt_pk_bf16(pe[6], pe[7]);
;         const bf16x8 pb = __builtin_bit_cast(bf16x8, pw);
; #pragma unroll
;         for (int dt = 0; dt < 4; ++dt) o[dt] = __builtin_amdgcn_mfma_f32_16x16x32_bf16(vf[c & 1][dt], pb, o[dt], 0, 0, 0);
;         __builtin_amdgcn_sched_barrier(0);
;     }
	v_max_f32_e32 v99, v99, v99
	v_max_f32_e32 v97, v97, v99
	v_sub_f32_e32 v99, 0xff800000, v97
	v_exp_f32_e32 v99, v99
	s_nop 0
	v_mul_f32_e32 v198, 0, v99
	v_mov_b32_e32 v199, v198
	v_mov_b32_e32 v200, v198
	v_mov_b32_e32 v201, v198
	v_mov_b32_e32 v206, v97
	v_mov_b32_e32 v207, v97
	v_mov_b32_e32 v208, s67
	v_mov_b32_e32 v209, s67
	v_mov_b32_e32 v210, 0
	v_mov_b32_e32 v211, 0
	v_pk_fma_f32 v[68:69], v[68:69], v[208:209], v[206:207] neg_lo:[0,0,1] neg_hi:[0,0,1]
	v_pk_fma_f32 v[70:71], v[70:71], v[208:209], v[206:207] neg_lo:[0,0,1] neg_hi:[0,0,1]
	v_exp_f32_e32 v68, v68
	v_pk_fma_f32 v[64:65], v[64:65], v[208:209], v[206:207] neg_lo:[0,0,1] neg_hi:[0,0,1]
	v_exp_f32_e32 v69, v69
	v_pk_fma_f32 v[66:67], v[66:67], v[208:209], v[206:207] neg_lo:[0,0,1] neg_hi:[0,0,1]
	v_exp_f32_e32 v70, v70
	v_exp_f32_e32 v71, v71
	v_exp_f32_e32 v212, v64
	v_pk_add_f32 v[210:211], v[210:211], v[68:69]
	v_exp_f32_e32 v213, v65
	v_pk_add_f32 v[210:211], v[210:211], v[70:71]
	v_exp_f32_e32 v214, v66
	v_exp_f32_e32 v215, v67
	v_pk_add_f32 v[210:211], v[210:211], v[212:213]
	v_cvt_pk_bf16_f32 v64, v68, v69
	v_pk_add_f32 v[210:211], v[210:211], v[214:215]
	v_cvt_pk_bf16_f32 v65, v70, v71
	v_cvt_pk_bf16_f32 v66, v212, v213
	v_cvt_pk_bf16_f32 v67, v214, v215
	s_nop 1
	v_mfma_f32_16x16x32_bf16 v[68:71], v[152:155], v[64:67], v[198:201]
	v_mfma_f32_16x16x32_bf16 v[152:155], v[170:173], v[64:67], v[198:201]
	v_mfma_f32_16x16x32_bf16 v[170:173], v[174:177], v[64:67], v[198:201]
	v_mfma_f32_16x16x32_bf16 v[64:67], v[178:181], v[64:67], v[198:201]
	ds_read_b128 v[174:177], v136 offset:32768
	ds_read_b128 v[178:181], v136 offset:40960
	s_nop 0
	ds_read_b128 v[198:201], v136 offset:49152
	ds_read_b128 v[202:205], v136 offset:57344
	v_pk_fma_f32 v[60:61], v[60:61], v[208:209], v[206:207] neg_lo:[0,0,1] neg_hi:[0,0,1]
	v_pk_fma_f32 v[62:63], v[62:63], v[208:209], v[206:207] neg_lo:[0,0,1] neg_hi:[0,0,1]
	v_exp_f32_e32 v60, v60
	v_pk_fma_f32 v[56:57], v[56:57], v[208:209], v[206:207] neg_lo:[0,0,1] neg_hi:[0,0,1]
	v_exp_f32_e32 v61, v61
	v_pk_fma_f32 v[58:59], v[58:59], v[208:209], v[206:207] neg_lo:[0,0,1] neg_hi:[0,0,1]
	v_exp_f32_e32 v62, v62
	v_exp_f32_e32 v63, v63
	v_exp_f32_e32 v212, v56
	v_pk_add_f32 v[210:211], v[210:211], v[60:61]
	v_exp_f32_e32 v213, v57
	v_pk_add_f32 v[210:211], v[210:211], v[62:63]
	v_exp_f32_e32 v214, v58
	v_exp_f32_e32 v215, v59
	v_pk_add_f32 v[210:211], v[210:211], v[212:213]
	v_cvt_pk_bf16_f32 v56, v60, v61
	v_pk_add_f32 v[210:211], v[210:211], v[214:215]
	v_cvt_pk_bf16_f32 v57, v62, v63
	v_cvt_pk_bf16_f32 v58, v212, v213
	v_cvt_pk_bf16_f32 v59, v214, v215
	s_nop 1
	v_mfma_f32_16x16x32_bf16 v[60:63], v[182:185], v[56:59], v[68:71]
	v_mfma_f32_16x16x32_bf16 v[68:71], v[186:189], v[56:59], v[152:155]
	v_mfma_f32_16x16x32_bf16 v[152:155], v[190:193], v[56:59], v[170:173]
	v_mfma_f32_16x16x32_bf16 v[56:59], v[194:197], v[56:59], v[64:67]
	s_nop 2
	ds_read_b128 v[64:67], v137 offset:32768
	ds_read_b128 v[170:173], v137 offset:40960
	ds_read_b128 v[182:185], v137 offset:49152
	ds_read_b128 v[186:189], v137 offset:57344
	v_pk_fma_f32 v[52:53], v[52:53], v[208:209], v[206:207] neg_lo:[0,0,1] neg_hi:[0,0,1]
	v_pk_fma_f32 v[54:55], v[54:55], v[208:209], v[206:207] neg_lo:[0,0,1] neg_hi:[0,0,1]
	v_exp_f32_e32 v52, v52
	v_pk_fma_f32 v[48:49], v[48:49], v[208:209], v[206:207] neg_lo:[0,0,1] neg_hi:[0,0,1]
	v_exp_f32_e32 v53, v53
	v_pk_fma_f32 v[50:51], v[50:51], v[208:209], v[206:207] neg_lo:[0,0,1] neg_hi:[0,0,1]
	v_exp_f32_e32 v54, v54
	v_exp_f32_e32 v55, v55
	v_exp_f32_e32 v212, v48
	v_pk_add_f32 v[210:211], v[210:211], v[52:53]
	v_exp_f32_e32 v213, v49
	v_pk_add_f32 v[210:211], v[210:211], v[54:55]
	v_exp_f32_e32 v214, v50
	v_exp_f32_e32 v215, v51
	v_pk_add_f32 v[210:211], v[210:211], v[212:213]
	v_cvt_pk_bf16_f32 v48, v52, v53
	v_pk_add_f32 v[210:211], v[210:211], v[214:215]
	v_cvt_pk_bf16_f32 v49, v54, v55
	v_cvt_pk_bf16_f32 v50, v212, v213
	v_cvt_pk_bf16_f32 v51, v214, v215
	s_waitcnt lgkmcnt(4)
	s_nop 0
	v_mfma_f32_16x16x32_bf16 v[52:55], v[174:177], v[48:51], v[60:63]
	v_mfma_f32_16x16x32_bf16 v[60:63], v[178:181], v[48:51], v[68:71]
	v_mfma_f32_16x16x32_bf16 v[68:71], v[198:201], v[48:51], v[152:155]
	v_mfma_f32_16x16x32_bf16 v[48:51], v[202:205], v[48:51], v[56:59]
	s_nop 2
	ds_read_b128 v[56:59], v138 offset:32768
	ds_read_b128 v[152:155], v138 offset:40960
	ds_read_b128 v[174:177], v138 offset:49152
	ds_read_b128 v[178:181], v138 offset:57344
	v_pk_fma_f32 v[44:45], v[44:45], v[208:209], v[206:207] neg_lo:[0,0,1] neg_hi:[0,0,1]
	v_pk_fma_f32 v[46:47], v[46:47], v[208:209], v[206:207] neg_lo:[0,0,1] neg_hi:[0,0,1]
	v_exp_f32_e32 v44, v44
	v_pk_fma_f32 v[40:41], v[40:41], v[208:209], v[206:207] neg_lo:[0,0,1] neg_hi:[0,0,1]
	v_exp_f32_e32 v45, v45
	v_pk_fma_f32 v[42:43], v[42:43], v[208:209], v[206:207] neg_lo:[0,0,1] neg_hi:[0,0,1]
	v_exp_f32_e32 v46, v46
	v_exp_f32_e32 v47, v47
	v_exp_f32_e32 v212, v40
	v_pk_add_f32 v[210:211], v[210:211], v[44:45]
	v_exp_f32_e32 v213, v41
	v_pk_add_f32 v[210:211], v[210:211], v[46:47]
	v_exp_f32_e32 v214, v42
	v_exp_f32_e32 v215, v43
	v_pk_add_f32 v[210:211], v[210:211], v[212:213]
	v_cvt_pk_bf16_f32 v40, v44, v45
	v_pk_add_f32 v[210:211], v[210:211], v[214:215]
	v_cvt_pk_bf16_f32 v41, v46, v47
	v_cvt_pk_bf16_f32 v42, v212, v213
	v_cvt_pk_bf16_f32 v43, v214, v215
	s_waitcnt lgkmcnt(4)
	s_nop 0
	v_mfma_f32_16x16x32_bf16 v[44:47], v[64:67], v[40:43], v[52:55]
	v_mfma_f32_16x16x32_bf16 v[52:55], v[170:173], v[40:43], v[60:63]
	v_mfma_f32_16x16x32_bf16 v[60:63], v[182:185], v[40:43], v[68:71]
	v_mfma_f32_16x16x32_bf16 v[40:43], v[186:189], v[40:43], v[48:51]
	s_nop 2
	ds_read_b128 v[48:51], v139 offset:32768
	ds_read_b128 v[64:67], v139 offset:40960
	ds_read_b128 v[68:71], v139 offset:49152
	ds_read_b128 v[170:173], v139 offset:57344
	s_and_b64 vcc, exec, s[74:75]
	s_cbranch_vccnz .Lkl_skip
; __device__ __forceinline__ unsigned cvt_pk_bf16(float lo, float hi) { const f32x2 v = (f32x2){lo, hi}; return __builtin_bit_cast(unsigned, __builtin_convertvector(v, bf16v2)); }
; #define AH_LDV(c, bufi) do { const int vaddr = vrow + (((vchunk0 + (c) * vcs + g) ^ qi) << 4); _Pragma("unroll") for (int dt = 0; dt < 4; ++dt) vf[bufi][dt] = *(const LAS bf16x8*)(lds + vaddr + dt * vpitch_dt); } while (0)
; template <bool LOC> ...
;     ...
;     for (int c = 0; c < 8; ++c) {
;         if (c < 7) AH_LDV(c + 1, (c + 1) & 1);
;         __builtin_amdgcn_sched_barrier(0);
;         float pe[8];
; #pragma unroll
;         for (int e = 0; e < 8; ++e) { pe[e] = __builtin_amdgcn_exp2f(s[c][e] - mx); lsum += pe[e]; }
;         u32x4 pw; pw.x = cvt_pk_bf16(pe[0], pe[1]); pw.y = cvt_pk_bf16(pe[2], pe[3]); pw.z = cvt_pk_bf16(pe[4], pe[5]); pw.w = cvt_pk_bf16(pe[6], pe[7]);
;         const bf16x8 pb = __builtin_bit_cast(bf16x8, pw);
; #pragma unroll
;         for (int dt = 0; dt < 4; ++dt) o[dt] = __builtin_amdgcn_mfma_f32_16x16x32_bf16(vf[c & 1][dt], pb, o[dt], 0, 0, 0);
;         __builtin_amdgcn_sched_barrier(0);
;     }
; __device__ __forceinline__ void phase_mixer(const Params& p, LAS unsigned char* lds, int l, bool with_ctx, int G, int tid, int wave, int lane, int rep_attn, int rep_pool) {
;     ...
;             const int tok0 = b * SEQ + rs0 * 64;
;             const bf16_t* ksrc = PB + (size_t)(tok0 + (tid >> 3)) * PBW + 1024 + h * 64 + (tid & 7) * 8;
;             u32x4 kreg[9], vreg[9];
; #pragma unroll
;             for (int ps = 0; ps < 9; ++ps) { const int idx = ps * 512 + tid, d = idx / 72, ch = idx - d * 72;
;                 kreg[ps] = *(const u32x4*)(ksrc + (size_t)(ps * 64) * PBW);
;                 vreg[ps] = *(const u32x4*)(VT + (size_t)(h * 64 + d) * VTP + tok0 + ch * 8); }
	v_sub_u32_e64 v248, s71, 4 clamp
	v_min_u32_e32 v248, 56, v248
	v_lshlrev_b32_e32 v248, 6, v248
	v_or_b32_e32 v248, s76, v248
	v_add_u32_e32 v248, v248, v109
	v_mov_b64_e32 v[250:251], s[0:1]
	v_mad_i64_i32 v[250:251], s[98:99], v248, s58, v[250:251]
	s_lshl_b32 s30, s70, 1
	v_lshl_add_u64 v[250:251], v[250:251], 0, s[30:31]
	v_lshl_add_u64 v[250:251], v[250:251], 0, v[156:157]
	s_mov_b32 s99, 0
	global_load_dwordx4 v[216:219], v[250:251], off offset:2048
	s_mov_b32 s98, 0x30000
	v_lshl_add_u64 v[224:225], v[250:251], 0, s[98:99]
	global_load_dwordx4 v[224:227], v[224:225], off offset:2048
	s_mov_b32 s98, 0x60000
	v_lshl_add_u64 v[228:229], v[250:251], 0, s[98:99]
	global_load_dwordx4 v[228:231], v[228:229], off offset:2048
	s_mov_b32 s98, 0x90000
	v_lshl_add_u64 v[190:191], v[250:251], 0, s[98:99]
	global_load_dwordx4 v[190:193], v[190:191], off offset:2048
	s_mov_b32 s98, 0xc0000
	v_lshl_add_u64 v[194:195], v[250:251], 0, s[98:99]
	global_load_dwordx4 v[194:197], v[194:195], off offset:2048
	s_mov_b32 s98, 0xf0000
	v_lshl_add_u64 v[198:199], v[250:251], 0, s[98:99]
	global_load_dwordx4 v[198:201], v[198:199], off offset:2048
	s_mov_b32 s98, 0x120000
	v_lshl_add_u64 v[202:203], v[250:251], 0, s[98:99]
	global_load_dwordx4 v[202:205], v[202:203], off offset:2048
	s_mov_b32 s98, 0x150000
	v_lshl_add_u64 v[182:183], v[250:251], 0, s[98:99]
	global_load_dwordx4 v[182:185], v[182:183], off offset:2048
	s_mov_b32 s98, 0x180000
	v_lshl_add_u64 v[186:187], v[250:251], 0, s[98:99]
	global_load_dwordx4 v[186:189], v[186:187], off offset:2048
.Lkl_skip:
	v_pk_fma_f32 v[36:37], v[36:37], v[208:209], v[206:207] neg_lo:[0,0,1] neg_hi:[0,0,1]
	v_pk_fma_f32 v[38:39], v[38:39], v[208:209], v[206:207] neg_lo:[0,0,1] neg_hi:[0,0,1]
	v_exp_f32_e32 v36, v36
	v_pk_fma_f32 v[32:33], v[32:33], v[208:209], v[206:207] neg_lo:[0,0,1] neg_hi:[0,0,1]
	v_exp_f32_e32 v37, v37
	v_pk_fma_f32 v[34:35], v[34:35], v[208:209], v[206:207] neg_lo:[0,0,1] neg_hi:[0,0,1]
	v_exp_f32_e32 v38, v38
	v_exp_f32_e32 v39, v39
	v_exp_f32_e32 v212, v32
	v_pk_add_f32 v[210:211], v[210:211], v[36:37]
	v_exp_f32_e32 v213, v33
	v_pk_add_f32 v[210:211], v[210:211], v[38:39]
	v_exp_f32_e32 v214, v34
	v_exp_f32_e32 v215, v35
	v_pk_add_f32 v[210:211], v[210:211], v[212:213]
	v_cvt_pk_bf16_f32 v32, v36, v37
	v_pk_add_f32 v[210:211], v[210:211], v[214:215]
	v_cvt_pk_bf16_f32 v33, v38, v39
	v_cvt_pk_bf16_f32 v34, v212, v213
	v_cvt_pk_bf16_f32 v35, v214, v215
	s_waitcnt lgkmcnt(4)
	s_nop 0
	v_mfma_f32_16x16x32_bf16 v[36:39], v[56:59], v[32:35], v[44:47]
	v_mfma_f32_16x16x32_bf16 v[44:47], v[152:155], v[32:35], v[52:55]
	v_mfma_f32_16x16x32_bf16 v[52:55], v[174:177], v[32:35], v[60:63]
	v_mfma_f32_16x16x32_bf16 v[32:35], v[178:181], v[32:35], v[40:43]
	s_nop 2
	ds_read_b128 v[40:43], v140 offset:32768
	ds_read_b128 v[56:59], v140 offset:40960
	ds_read_b128 v[60:63], v140 offset:49152
	ds_read_b128 v[152:155], v140 offset:57344
	v_pk_fma_f32 v[28:29], v[28:29], v[208:209], v[206:207] neg_lo:[0,0,1] neg_hi:[0,0,1]
	v_pk_fma_f32 v[30:31], v[30:31], v[208:209], v[206:207] neg_lo:[0,0,1] neg_hi:[0,0,1]
	v_exp_f32_e32 v28, v28
	v_pk_fma_f32 v[24:25], v[24:25], v[208:209], v[206:207] neg_lo:[0,0,1] neg_hi:[0,0,1]
	v_exp_f32_e32 v29, v29
	v_pk_fma_f32 v[26:27], v[26:27], v[208:209], v[206:207] neg_lo:[0,0,1] neg_hi:[0,0,1]
	v_exp_f32_e32 v30, v30
	v_exp_f32_e32 v31, v31
	v_exp_f32_e32 v212, v24
	v_pk_add_f32 v[210:211], v[210:211], v[28:29]
	v_exp_f32_e32 v213, v25
	v_pk_add_f32 v[210:211], v[210:211], v[30:31]
	v_exp_f32_e32 v214, v26
	v_exp_f32_e32 v215, v27
	v_pk_add_f32 v[210:211], v[210:211], v[212:213]
	v_cvt_pk_bf16_f32 v24, v28, v29
	v_pk_add_f32 v[210:211], v[210:211], v[214:215]
	v_cvt_pk_bf16_f32 v25, v30, v31
	v_cvt_pk_bf16_f32 v26, v212, v213
	v_cvt_pk_bf16_f32 v27, v214, v215
	s_waitcnt lgkmcnt(4)
	s_nop 0
	v_mfma_f32_16x16x32_bf16 v[28:31], v[48:51], v[24:27], v[36:39]
	v_mfma_f32_16x16x32_bf16 v[36:39], v[64:67], v[24:27], v[44:47]
	v_mfma_f32_16x16x32_bf16 v[44:47], v[68:71], v[24:27], v[52:55]
	v_mfma_f32_16x16x32_bf16 v[24:27], v[170:173], v[24:27], v[32:35]
	s_nop 2
	ds_read_b128 v[32:35], v141 offset:32768
	ds_read_b128 v[48:51], v141 offset:40960
	ds_read_b128 v[52:55], v141 offset:49152
	ds_read_b128 v[64:67], v141 offset:57344
	v_pk_fma_f32 v[20:21], v[20:21], v[208:209], v[206:207] neg_lo:[0,0,1] neg_hi:[0,0,1]
	v_pk_fma_f32 v[22:23], v[22:23], v[208:209], v[206:207] neg_lo:[0,0,1] neg_hi:[0,0,1]
	v_exp_f32_e32 v20, v20
	v_pk_fma_f32 v[16:17], v[16:17], v[208:209], v[206:207] neg_lo:[0,0,1] neg_hi:[0,0,1]
	v_exp_f32_e32 v21, v21
	v_pk_fma_f32 v[18:19], v[18:19], v[208:209], v[206:207] neg_lo:[0,0,1] neg_hi:[0,0,1]
	v_exp_f32_e32 v22, v22
	v_exp_f32_e32 v23, v23
	v_exp_f32_e32 v212, v16
	v_pk_add_f32 v[210:211], v[210:211], v[20:21]
	v_exp_f32_e32 v213, v17
	v_pk_add_f32 v[210:211], v[210:211], v[22:23]
	v_exp_f32_e32 v214, v18
	v_exp_f32_e32 v215, v19
	v_pk_add_f32 v[210:211], v[210:211], v[212:213]
	v_cvt_pk_bf16_f32 v16, v20, v21
	v_pk_add_f32 v[210:211], v[210:211], v[214:215]
	v_cvt_pk_bf16_f32 v17, v22, v23
	v_cvt_pk_bf16_f32 v18, v212, v213
	v_cvt_pk_bf16_f32 v19, v214, v215
	s_waitcnt lgkmcnt(4)
	s_nop 0
	v_mfma_f32_16x16x32_bf16 v[20:23], v[40:43], v[16:19], v[28:31]
	v_mfma_f32_16x16x32_bf16 v[36:39], v[56:59], v[16:19], v[36:39]
	v_mfma_f32_16x16x32_bf16 v[40:43], v[60:63], v[16:19], v[44:47]
	v_mfma_f32_16x16x32_bf16 v[24:27], v[152:155], v[16:19], v[24:27]
	v_pk_fma_f32 v[12:13], v[12:13], v[208:209], v[206:207] neg_lo:[0,0,1] neg_hi:[0,0,1]
	v_pk_fma_f32 v[14:15], v[14:15], v[208:209], v[206:207] neg_lo:[0,0,1] neg_hi:[0,0,1]
	v_exp_f32_e32 v12, v12
	v_pk_fma_f32 v[8:9], v[8:9], v[208:209], v[206:207] neg_lo:[0,0,1] neg_hi:[0,0,1]
	v_exp_f32_e32 v13, v13
	v_pk_fma_f32 v[10:11], v[10:11], v[208:209], v[206:207] neg_lo:[0,0,1] neg_hi:[0,0,1]
	v_exp_f32_e32 v14, v14
	v_exp_f32_e32 v15, v15
	v_exp_f32_e32 v212, v8
	v_pk_add_f32 v[210:211], v[210:211], v[12:13]
	v_exp_f32_e32 v213, v9
	v_pk_add_f32 v[210:211], v[210:211], v[14:15]
	v_exp_f32_e32 v214, v10
	v_exp_f32_e32 v215, v11
	v_pk_add_f32 v[210:211], v[210:211], v[212:213]
	v_cvt_pk_bf16_f32 v44, v12, v13
	v_pk_add_f32 v[210:211], v[210:211], v[214:215]
	v_cvt_pk_bf16_f32 v45, v14, v15
	v_cvt_pk_bf16_f32 v46, v212, v213
	v_cvt_pk_bf16_f32 v47, v214, v215
	v_add_f32_e32 v28, v210, v211
	s_waitcnt lgkmcnt(0)
	v_mfma_f32_16x16x32_bf16 v[8:11], v[32:35], v[44:47], v[20:23]
	v_mfma_f32_16x16x32_bf16 v[12:15], v[48:51], v[44:47], v[36:39]
	v_mfma_f32_16x16x32_bf16 v[16:19], v[52:55], v[44:47], v[40:43]
	v_mfma_f32_16x16x32_bf16 v[20:23], v[64:67], v[44:47], v[24:27]
	s_andn2_b64 vcc, exec, s[74:75]
	s_mov_b64 s[68:69], -1
	s_cbranch_vccnz .LBB0_298
; #define LAS __attribute__((address_space(3)))
; __device__ __forceinline__ unsigned cvt_pk_bf16(float lo, float hi) { const f32x2 v = (f32x2){lo, hi}; return __builtin_bit_cast(unsigned, __builtin_convertvector(v, bf16v2)); }
; __device__ __forceinline__ int kswz(int key) { return ((key >> 1) & 1) | (((key >> 3) & 3) << 1); }
; __device__ __forceinline__ void attn_store(bf16_t* MIX, int qtok, int h, int g, float lsum, const f32x4 (&o)[4]) {
;     lsum += __shfl_xor(lsum, 16); lsum += __shfl_xor(lsum, 32);
;     const float inv = 1.f / lsum;
;     bf16_t* op = MIX + (size_t)qtok * DM + 512 + h * 64 + 4 * g;
; #pragma unroll
;     for (int dt = 0; dt < 4; ++dt) { u32x2 w; w.x = cvt_pk_bf16(o[dt][0] * inv, o[dt][1] * inv); w.y = cvt_pk_bf16(o[dt][2] * inv, o[dt][3] * inv); *(u32x2*)(op + 16 * dt) = w; }
; }
; __device__ __forceinline__ void phase_mixer(const Params& p, LAS unsigned char* lds, int l, bool with_ctx, int G, int tid, int wave, int lane, int rep_attn, int rep_pool) {
;     ...
;             const int tok0 = b * SEQ + rs0 * 64;
;             const bf16_t* ksrc = PB + (size_t)(tok0 + (tid >> 3)) * PBW + 1024 + h * 64 + (tid & 7) * 8;
;             u32x4 kreg[9], vreg[9];
; #pragma unroll
;             for (int ps = 0; ps < 9; ++ps) { const int idx = ps * 512 + tid, d = idx / 72, ch = idx - d * 72;
;                 kreg[ps] = *(const u32x4*)(ksrc + (size_t)(ps * 64) * PBW);
;                 vreg[ps] = *(const u32x4*)(VT + (size_t)(h * 64 + d) * VTP + tok0 + ch * 8); }
;             __builtin_amdgcn_sched_barrier(0);
; #pragma unroll
;             for (int ps = 0; ps < 9; ++ps) { const int key = ps * 64 + (tid >> 3), idx = ps * 512 + tid, d = idx / 72, ch = idx - d * 72;
;                 *(LAS u32x4*)(lds + AT_KL + key * 128 + ((((tid & 7) ^ kswz(key))) << 4)) = kreg[ps];
;                 *(LAS u32x4*)(lds + AT_VL + d * AT_VLP + ((ch ^ (d & 15)) << 4)) = vreg[ps]; }
	ds_bpermute_b32 v24, v114, v28
	v_ashrrev_i32_e32 v105, 31, v104
	s_waitcnt lgkmcnt(0)
	v_add_f32_e32 v24, v28, v24
	ds_bpermute_b32 v25, v115, v24
	s_waitcnt lgkmcnt(0)
	v_add_f32_e32 v24, v24, v25
	v_div_scale_f32 v25, s[68:69], v24, v24, 1.0
	v_rcp_f32_e32 v26, v25
	s_mov_b64 s[68:69], 0
	v_fma_f32 v27, -v25, v26, 1.0
	v_fmac_f32_e32 v26, v27, v26
	v_div_scale_f32 v27, vcc, 1.0, v24, 1.0
	v_mul_f32_e32 v29, v27, v26
	v_fma_f32 v30, -v25, v29, v27
	v_fmac_f32_e32 v29, v30, v26
	v_fma_f32 v25, -v25, v29, v27
	v_div_fmas_f32 v25, v25, v26, v29
	v_div_fixup_f32 v24, v25, v24, 1.0
	v_lshlrev_b64 v[26:27], 11, v[104:105]
	v_pk_mul_f32 v[30:31], v[8:9], v[24:25] op_sel_hi:[1,0]
	v_pk_mul_f32 v[32:33], v[10:11], v[24:25] op_sel_hi:[1,0]
	v_lshl_add_u64 v[26:27], v[102:103], 0, v[26:27]
	v_cvt_pk_bf16_f32 v30, v30, v31
	v_cvt_pk_bf16_f32 v31, v32, v33
	global_store_dwordx2 v[26:27], v[30:31], off offset:1024
	v_pk_mul_f32 v[30:31], v[12:13], v[24:25] op_sel_hi:[1,0]
	v_pk_mul_f32 v[32:33], v[14:15], v[24:25] op_sel_hi:[1,0]
	v_cvt_pk_bf16_f32 v30, v30, v31
	v_cvt_pk_bf16_f32 v31, v32, v33
	global_store_dwordx2 v[26:27], v[30:31], off offset:1056
	v_pk_mul_f32 v[30:31], v[16:17], v[24:25] op_sel_hi:[1,0]
	v_pk_mul_f32 v[32:33], v[18:19], v[24:25] op_sel_hi:[1,0]
	v_cvt_pk_bf16_f32 v30, v30, v31
	v_cvt_pk_bf16_f32 v31, v32, v33
	global_store_dwordx2 v[26:27], v[30:31], off offset:1088
	v_pk_mul_f32 v[30:31], v[20:21], v[24:25] op_sel_hi:[1,0]
	v_pk_mul_f32 v[24:25], v[22:23], v[24:25] op_sel_hi:[1,0]
	v_cvt_pk_bf16_f32 v30, v30, v31
	v_cvt_pk_bf16_f32 v31, v24, v25
	global_store_dwordx2 v[26:27], v[30:31], off offset:1120
	s_branch .LBB0_298
.LBB0_301:
	v_sub_u32_e64 v24, s71, 4 clamp
	v_min_u32_e32 v26, 56, v24
	s_barrier
	s_waitcnt vmcnt(8)
	ds_write_b128 v111, v[216:219]
	s_waitcnt vmcnt(7)
	ds_write_b128 v111, v[224:227] offset:8192
	s_waitcnt vmcnt(6)
	ds_write_b128 v111, v[228:231] offset:16384
	s_waitcnt vmcnt(5)
	ds_write_b128 v111, v[190:193] offset:24576
	s_waitcnt vmcnt(4)
	ds_write_b128 v111, v[194:197] offset:32768
	s_waitcnt vmcnt(3)
	ds_write_b128 v111, v[198:201] offset:40960
	s_waitcnt vmcnt(2)
	ds_write_b128 v111, v[202:205] offset:49152
	s_waitcnt vmcnt(1)
	ds_write_b128 v111, v[182:185] offset:57344
	s_waitcnt vmcnt(0)
	ds_write_b128 v125, v[186:189]
	s_mov_b32 s80, 0x3a800000
	s_mov_b64 s[68:69], exec
	s_cmp_eq_u32 s61, s2
	s_cbranch_scc1 .Lrpb_load
	s_and_b32 s32, s3, 7
	s_cmp_eq_u32 s32, 0
	s_cbranch_scc1 .LBB0_296
